# v35 + differential QK: first S1 MFMA issued between the S0 pairs (S0 S0 S1 S0 S0, then row max of S0 beside the remaining S1 MFMAs)
# speedup vs baseline: 1.0023x; 1.0023x over previous
; #define A2_WAITN(n) asm volatile("s_waitcnt vmcnt(%0)" :: "n"(n) : "memory")
; #define A2_BAR() do { __builtin_amdgcn_s_barrier(); asm volatile("" ::: "memory"); } while (0)
; #define A2_SETKC(SOFF) _Pragma("unroll") for (int _i = 0; _i < NKB; ++_i) kc[_i] = kbase[_i] + (unsigned)(SOFF)
; #define A2_SETVC(SOFF) _Pragma("unroll") for (int _i = 0; _i < 4; ++_i) vc[_i] = vbase[_i] + (unsigned)(SOFF)
; template <int TYPE>
; __device__ __forceinline__ void attn_mfma_unit2(const AttnCtx& A, unsigned char* ws, LAS unsigned char* lds, int tid, const AUnit& u) {
;     ...
;         for (int ti = 0; ti < nt; ++ti) {
;             if (ti + 1 < nt) A2_DMA(ti + 1, snxt);
;             if (actP) { A2_SETVC(sprv); A2_FSM_PV(sA0, sA1, 0); }
;             actP = A2_ACTIVE(ti);
;             if (actP) { A2_SETKC(scur); A2_QK(sA0, sA1, ti, 0); A2_PSM(sA0, sA1); }
;             A2_WAITN(0); A2_BAR();
.LBB0_2781:
	s_add_i32 s46, s15, 1
	s_cmp_lt_u32 s15, 3
	s_cselect_b32 s48, s46, s15
	s_cselect_b32 s49, s38, s39
	s_lshl_b32 s48, s48, 6
	s_add_i32 s48, s48, s49
	s_ashr_i32 s49, s48, 31
	s_lshl_b64 s[50:51], s[48:49], 1
	s_add_u32 s50, s12, s50
	v_mad_i64_i32 v[2:3], s[48:49], s48, v242, v[132:133]
	s_addc_u32 s51, s13, s51
	s_add_i32 s48, s14, s6
	s_mov_b32 m0, s48
	s_nop 0
	global_load_lds_dwordx4 v[2:3], off
	s_add_i32 m0, s48, 0x2000
	v_lshl_add_u64 v[2:3], v[128:129], 1, s[50:51]
	global_load_lds_dwordx4 v[2:3], off
	v_lshl_add_u64 v[2:3], v[130:131], 1, s[50:51]
	s_add_i32 m0, s48, 0x4000
	s_mov_b32 s48, s7
	global_load_lds_dwordx4 v[2:3], off
	v_add_u32_e32 v0, s48, v137
	ds_read_b128 v[2:5], v0 offset:8192
	ds_read_b128 v[6:9], v0 offset:12288
	ds_read_b128 v[10:13], v0 offset:16384
	ds_read_b128 v[140:143], v0 offset:20480
	s_mov_b32 s7, s47
	v_exp_f32_e32 v14, v96
	v_exp_f32_e32 v144, v97
	v_exp_f32_e32 v98, v98
	v_exp_f32_e32 v146, v99
	v_exp_f32_e32 v15, v100
	v_exp_f32_e32 v145, v101
	v_exp_f32_e32 v99, v102
	v_exp_f32_e32 v147, v103
	v_add_u32_e32 v0, s48, v136
	v_pk_add_f32 v[96:97], v[14:15], v[144:145]
	v_pk_add_f32 v[100:101], v[98:99], v[146:147]
	s_nop 0
	v_pk_add_f32 v[96:97], v[96:97], v[100:101]
	v_cvt_pk_bf16_f32 v99, v99, v147
	v_pk_add_f32 v[156:157], v[96:97], v[96:97] op_sel_hi:[0,1]
	v_cvt_pk_bf16_f32 v96, v14, v144
	v_cvt_pk_bf16_f32 v97, v98, v146
	v_cvt_pk_bf16_f32 v98, v15, v145
	ds_read_b128 v[100:103], v0 offset:8192
	ds_read_b128 v[144:147], v0 offset:12288
	ds_read_b128 v[148:151], v0 offset:16384
	ds_read_b128 v[152:155], v0 offset:20480
	s_waitcnt lgkmcnt(0)
	v_mfma_f32_32x32x16_bf16 v[64:79], v[2:5], v[96:99], v[64:79]
	v_mfma_f32_32x32x16_bf16 v[48:63], v[6:9], v[96:99], v[48:63]
	v_mfma_f32_32x32x16_bf16 v[32:47], v[10:13], v[96:99], v[32:47]
	v_mfma_f32_32x32x16_bf16 v[16:31], v[140:143], v[96:99], v[16:31]
	v_exp_f32_e32 v2, v104
	v_exp_f32_e32 v4, v105
	v_exp_f32_e32 v3, v106
	v_exp_f32_e32 v5, v107
	v_exp_f32_e32 v6, v108
	v_exp_f32_e32 v8, v109
	v_exp_f32_e32 v7, v110
	v_exp_f32_e32 v9, v111
	v_pk_add_f32 v[10:11], v[2:3], v[4:5]
	v_add_u32_e32 v0, s48, v135
	v_pk_add_f32 v[14:15], v[10:11], v[10:11] op_sel_hi:[0,1]
	v_pk_add_f32 v[10:11], v[6:7], v[8:9]
	v_cvt_pk_bf16_f32 v2, v2, v4
	v_pk_add_f32 v[140:141], v[10:11], v[10:11] op_sel_hi:[0,1]
	v_cvt_pk_bf16_f32 v3, v3, v5
	v_cvt_pk_bf16_f32 v4, v6, v8
	v_cvt_pk_bf16_f32 v5, v7, v9
	ds_read_b128 v[6:9], v0 offset:8192
	ds_read_b128 v[10:13], v0 offset:12288
	ds_read_b128 v[96:99], v0 offset:16384
	ds_read_b128 v[104:107], v0 offset:20480
	v_mfma_f32_32x32x16_bf16 v[64:79], v[100:103], v[2:5], v[64:79]
	v_mfma_f32_32x32x16_bf16 v[48:63], v[144:147], v[2:5], v[48:63]
	v_mfma_f32_32x32x16_bf16 v[32:47], v[148:151], v[2:5], v[32:47]
	v_mfma_f32_32x32x16_bf16 v[16:31], v[152:155], v[2:5], v[16:31]
	v_exp_f32_e32 v0, v80
	v_exp_f32_e32 v2, v81
	v_exp_f32_e32 v3, v82
	v_exp_f32_e32 v4, v83
	v_exp_f32_e32 v5, v84
	v_exp_f32_e32 v14, v85
	v_exp_f32_e32 v80, v86
	v_exp_f32_e32 v81, v87
	v_add_f32_e32 v143, v0, v2
	v_cvt_pk_bf16_f32 v2, v0, v2
	v_add_u32_e32 v0, s48, v134
	v_add_f32_e32 v145, v3, v4
	v_add_f32_e32 v147, v5, v14
	v_add_f32_e32 v149, v80, v81
	v_cvt_pk_bf16_f32 v3, v3, v4
	v_cvt_pk_bf16_f32 v4, v5, v14
	v_cvt_pk_bf16_f32 v5, v80, v81
	ds_read_b128 v[80:83], v0 offset:8192
	ds_read_b128 v[84:87], v0 offset:12288
	ds_read_b128 v[100:103], v0 offset:16384
	ds_read_b128 v[108:111], v0 offset:20480
	s_waitcnt lgkmcnt(0)
	v_mfma_f32_32x32x16_bf16 v[64:79], v[6:9], v[2:5], v[64:79]
	v_mfma_f32_32x32x16_bf16 v[48:63], v[10:13], v[2:5], v[48:63]
	v_mfma_f32_32x32x16_bf16 v[32:47], v[96:99], v[2:5], v[32:47]
	v_mfma_f32_32x32x16_bf16 v[16:31], v[104:107], v[2:5], v[16:31]
	v_exp_f32_e32 v142, v88
	v_exp_f32_e32 v144, v89
	v_exp_f32_e32 v146, v90
	v_exp_f32_e32 v148, v91
	v_exp_f32_e32 v14, v92
	v_exp_f32_e32 v140, v93
	v_exp_f32_e32 v156, v94
	v_exp_f32_e32 v0, v95
	v_cvt_pk_bf16_f32 v2, v142, v144
	v_cvt_pk_bf16_f32 v3, v146, v148
	v_cvt_pk_bf16_f32 v4, v14, v140
	v_cvt_pk_bf16_f32 v5, v156, v0
	s_nop 1
	v_mfma_f32_32x32x16_bf16 v[64:79], v[80:83], v[2:5], v[64:79]
	v_add_f32_e64 v6, v142, v144
	v_add_f32_e64 v7, v143, v145
	v_add_f32_e64 v8, v146, v148
	v_add_f32_e64 v9, v147, v149
	v_add_f32_e64 v10, v156, v0
	v_add_f32_e64 v11, v157, v1
	v_pk_add_f32 v[6:7], v[6:7], v[8:9]
	v_pk_add_f32 v[8:9], v[14:15], v[140:141]
	s_nop 0
	v_pk_add_f32 v[8:9], v[8:9], v[10:11]
	v_mfma_f32_32x32x16_bf16 v[48:63], v[84:87], v[2:5], v[48:63]
	v_add_f32_e64 v6, v6, v8
	v_add_f32_e64 v7, v7, v9
	v_pk_add_f32 v[6:7], v[6:7], v[6:7] op_sel:[0,1] op_sel_hi:[1,0]
	v_mfma_f32_32x32x16_bf16 v[32:47], v[100:103], v[2:5], v[32:47]
	v_mfma_f32_32x32x16_bf16 v[16:31], v[108:111], v[2:5], v[16:31]
	v_mov_b32_e32 v0, v6
	s_nop 1
	v_permlane32_swap_b32_e32 v6, v0
	v_add_f32_e32 v0, v6, v0
	v_add_f32_e32 v139, v139, v0
	v_add_u32_e32 v0, s7, v137
	ds_read_b128 v[2:5], v0
	ds_read_b128 v[6:9], v0 offset:4096
	v_add_u32_e32 v0, s7, v136
	ds_read_b128 v[10:13], v0
	ds_read_b128 v[140:143], v0 offset:4096
	v_add_u32_e32 v0, s7, v135
	v_add_u32_e32 v14, s7, v134
	ds_read_b128 v[144:147], v0
	ds_read_b128 v[148:151], v0 offset:4096
	ds_read_b128 v[152:155], v14
	ds_read_b128 v[156:159], v14 offset:4096
	v_xor_b32_e32 v80, 0x80000000, v138
	v_mov_b32_e32 v81, v80
	v_mov_b32_e32 v82, v80
	v_mov_b32_e32 v83, v80
	v_mov_b32_e32 v84, v80
	v_mov_b32_e32 v85, v80
	v_mov_b32_e32 v86, v80
	v_mov_b32_e32 v87, v80
	v_mov_b32_e32 v88, v80
	v_mov_b32_e32 v89, v80
	v_mov_b32_e32 v90, v80
	v_mov_b32_e32 v91, v80
	v_mov_b32_e32 v92, v80
	v_mov_b32_e32 v93, v80
	v_mov_b32_e32 v94, v80
	v_mov_b32_e32 v95, v80
	s_waitcnt lgkmcnt(0)
	s_nop 0
	v_mfma_f32_32x32x16_bf16 v[96:111], v[2:5], v[124:127], v[80:95]
	v_mfma_f32_32x32x16_bf16 v[96:111], v[10:13], v[120:123], v[96:111]
	v_mfma_f32_32x32x16_bf16 v[80:95], v[6:9], v[124:127], v[80:95]
	v_mfma_f32_32x32x16_bf16 v[96:111], v[144:147], v[116:119], v[96:111]
	v_mfma_f32_32x32x16_bf16 v[96:111], v[152:155], v[112:115], v[96:111]
	s_nop 14
	v_max_f32_e32 v0, v97, v97
	v_max_f32_e32 v2, v96, v96
	v_max_f32_e32 v0, v2, v0
	v_max3_f32 v0, v0, v98, v99
	v_max3_f32 v0, v0, v100, v101
	v_max3_f32 v0, v0, v102, v103
	v_max3_f32 v0, v0, v104, v105
	v_mfma_f32_32x32x16_bf16 v[80:95], v[140:143], v[120:123], v[80:95]
	v_max3_f32 v0, v0, v106, v107
	v_max3_f32 v0, v0, v108, v109
	v_max3_f32 v0, v0, v110, v111
	s_mov_b32 s47, 0x41000000
	v_mfma_f32_32x32x16_bf16 v[80:95], v[148:151], v[116:119], v[80:95]
	v_mfma_f32_32x32x16_bf16 v[80:95], v[156:159], v[112:115], v[80:95]
	s_nop 11
	v_max3_f32 v0, v0, v80, v81
	v_max3_f32 v0, v0, v82, v83
	v_max3_f32 v0, v0, v84, v85
	v_max3_f32 v0, v0, v86, v87
	v_max3_f32 v0, v0, v88, v89
	v_max3_f32 v0, v0, v90, v91
	v_max3_f32 v0, v0, v92, v93
	v_max3_f32 v0, v0, v94, v95
	v_mov_b32_e32 v2, v0
	s_nop 1
	v_permlane32_swap_b32_e32 v0, v2
	v_max_f32_e32 v2, v2, v2
	v_max_f32_e32 v0, v0, v0
	v_max_f32_e32 v0, v0, v2
	v_cmp_ge_f32_e32 vcc, s47, v0
	s_cmp_eq_u64 vcc, exec
	s_cbranch_scc1 .LBB0_2783
	v_max_f32_e32 v0, v0, v0
	v_max_f32_e32 v2, 0, v0
	v_exp_f32_e64 v0, -v2
	v_add_f32_e32 v138, v138, v2
	v_sub_f32_e32 v111, v111, v2
	v_sub_f32_e32 v110, v110, v2
	v_pk_mul_f32 v[78:79], v[78:79], v[0:1] op_sel_hi:[1,0]
	v_pk_mul_f32 v[76:77], v[76:77], v[0:1] op_sel_hi:[1,0]
	v_pk_mul_f32 v[74:75], v[74:75], v[0:1] op_sel_hi:[1,0]
	v_pk_mul_f32 v[72:73], v[72:73], v[0:1] op_sel_hi:[1,0]
	v_pk_mul_f32 v[70:71], v[70:71], v[0:1] op_sel_hi:[1,0]
	v_pk_mul_f32 v[68:69], v[68:69], v[0:1] op_sel_hi:[1,0]
	v_pk_mul_f32 v[66:67], v[66:67], v[0:1] op_sel_hi:[1,0]
	v_pk_mul_f32 v[64:65], v[64:65], v[0:1] op_sel_hi:[1,0]
	v_pk_mul_f32 v[62:63], v[62:63], v[0:1] op_sel_hi:[1,0]
	v_pk_mul_f32 v[60:61], v[60:61], v[0:1] op_sel_hi:[1,0]
	v_pk_mul_f32 v[58:59], v[58:59], v[0:1] op_sel_hi:[1,0]
	v_pk_mul_f32 v[56:57], v[56:57], v[0:1] op_sel_hi:[1,0]
	v_pk_mul_f32 v[54:55], v[54:55], v[0:1] op_sel_hi:[1,0]
	v_pk_mul_f32 v[52:53], v[52:53], v[0:1] op_sel_hi:[1,0]
	v_pk_mul_f32 v[50:51], v[50:51], v[0:1] op_sel_hi:[1,0]
	v_pk_mul_f32 v[48:49], v[48:49], v[0:1] op_sel_hi:[1,0]
	v_pk_mul_f32 v[46:47], v[46:47], v[0:1] op_sel_hi:[1,0]
	v_pk_mul_f32 v[44:45], v[44:45], v[0:1] op_sel_hi:[1,0]
	v_pk_mul_f32 v[42:43], v[42:43], v[0:1] op_sel_hi:[1,0]
	v_pk_mul_f32 v[40:41], v[40:41], v[0:1] op_sel_hi:[1,0]
	v_pk_mul_f32 v[38:39], v[38:39], v[0:1] op_sel_hi:[1,0]
	v_pk_mul_f32 v[36:37], v[36:37], v[0:1] op_sel_hi:[1,0]
	v_pk_mul_f32 v[34:35], v[34:35], v[0:1] op_sel_hi:[1,0]
	v_pk_mul_f32 v[32:33], v[32:33], v[0:1] op_sel_hi:[1,0]
	v_pk_mul_f32 v[30:31], v[30:31], v[0:1] op_sel_hi:[1,0]
	v_pk_mul_f32 v[28:29], v[28:29], v[0:1] op_sel_hi:[1,0]
	v_pk_mul_f32 v[26:27], v[26:27], v[0:1] op_sel_hi:[1,0]
	v_pk_mul_f32 v[24:25], v[24:25], v[0:1] op_sel_hi:[1,0]
	v_pk_mul_f32 v[22:23], v[22:23], v[0:1] op_sel_hi:[1,0]
	v_pk_mul_f32 v[20:21], v[20:21], v[0:1] op_sel_hi:[1,0]
	v_pk_mul_f32 v[18:19], v[18:19], v[0:1] op_sel_hi:[1,0]
	v_pk_mul_f32 v[16:17], v[16:17], v[0:1] op_sel_hi:[1,0]
	v_sub_f32_e32 v109, v109, v2
	v_sub_f32_e32 v108, v108, v2
	v_sub_f32_e32 v107, v107, v2
	v_sub_f32_e32 v106, v106, v2
	v_sub_f32_e32 v105, v105, v2
	v_sub_f32_e32 v104, v104, v2
	v_sub_f32_e32 v103, v103, v2
	v_sub_f32_e32 v102, v102, v2
	v_sub_f32_e32 v101, v101, v2
	v_sub_f32_e32 v100, v100, v2
	v_sub_f32_e32 v99, v99, v2
	v_sub_f32_e32 v98, v98, v2
	v_sub_f32_e32 v97, v97, v2
	v_sub_f32_e32 v96, v96, v2
	v_sub_f32_e32 v95, v95, v2
	v_sub_f32_e32 v94, v94, v2
	v_sub_f32_e32 v93, v93, v2
	v_sub_f32_e32 v92, v92, v2
	v_sub_f32_e32 v91, v91, v2
	v_sub_f32_e32 v90, v90, v2
	v_sub_f32_e32 v89, v89, v2
	v_sub_f32_e32 v88, v88, v2
	v_sub_f32_e32 v87, v87, v2
	v_sub_f32_e32 v86, v86, v2
	v_sub_f32_e32 v85, v85, v2
	v_sub_f32_e32 v84, v84, v2
	v_sub_f32_e32 v83, v83, v2
	v_sub_f32_e32 v82, v82, v2
	v_sub_f32_e32 v81, v81, v2
	v_sub_f32_e32 v80, v80, v2
	v_mul_f32_e32 v139, v139, v0
